# out-projection epilogue: residual (x) rows of all 8 row blocks touched up front so the serial load-add-store rungs hit in cache (prompt groups); on top of zero-once + MLA K read-ahead
# baseline (speedup 1.0000x reference)
; __device__ __forceinline__ void st_bf8(bf16* p, f32x4 a, f32x4 b) { u32x4 w; w.x = pk2(a[0], a[1]); w.y = pk2(a[2], a[3]); w.z = pk2(b[0], b[1]); w.w = pk2(b[2], b[3]); *(u32x4*)p = w; }
;     __device__ __forceinline__ void operator()(AccRef acc, const pg8::Unit& u, int wr, int wc, int fr, int fq) const {
;         const int c0 = u.pn * 256;
; #pragma unroll
;         for (int ai = 0; ai < 2; ++ai)
; #pragma unroll
;             for (int m = 0; m < 4; ++m) {
;                 const int row = u.pm * 256 + ai * 128 + wr * 64 + m * 16 + fr; const size_t rw = (size_t)row; const bool ok = row < nvalid;
;                 float s = 0.f;
; #pragma unroll
;                 for (int bj = 0; bj < 2; ++bj) {
;                     const int cl = bj * 128 + wc * 32 + 8 * fq;
;                     f32x4 v0 = {0.f, 0.f, 0.f, 0.f}, v1 = {0.f, 0.f, 0.f, 0.f};
;                     if (ok) { const float* xb = x + rw * 1024 + c0 + cl; v0 = *(const f32x4*)xb + acc[ai][bj][m][0]; v1 = *(const f32x4*)(xb + 4) + acc[ai][bj][m][1]; }
;                     st_bf8(XB + rw * 1024 + c0 + cl, v0, v1);
.LBB0_383:
	v_lshl_add_u32 v144, s54, 8, v137
	v_ashrrev_i32_e32 v145, 31, v144
	s_lshl_b32 s24, s51, 8
	v_lshlrev_b64 v[142:143], 12, v[144:145]
	s_ashr_i32 s25, s24, 31
	v_lshl_add_u64 v[142:143], s[6:7], 0, v[142:143]
	v_cmp_gt_i32_e32 vcc, s28, v144
	v_mov_b32_e32 v146, 0
	v_lshl_add_u64 v[156:157], s[24:25], 2, v[142:143]
	v_lshlrev_b32_e32 v142, 2, v136
	v_readlane_b32 s98, v247, 61
	s_cmp_eq_u32 s98, 0
	s_cbranch_scc1 .Lpf_out_skip
	v_mov_b32_e32 v238, v142
	v_mov_b32_e32 v239, 0
	v_lshl_add_u64 v[240:241], v[156:157], 0, v[238:239]
	s_mov_b64 s[98:99], 0x10000
	global_load_dword v242, v[240:241], off
	global_load_dword v242, v[240:241], off offset:512
	v_lshl_add_u64 v[240:241], v[240:241], 0, s[98:99]
	global_load_dword v242, v[240:241], off
	global_load_dword v242, v[240:241], off offset:512
	v_lshl_add_u64 v[240:241], v[240:241], 0, s[98:99]
	global_load_dword v242, v[240:241], off
	global_load_dword v242, v[240:241], off offset:512
	v_lshl_add_u64 v[240:241], v[240:241], 0, s[98:99]
	global_load_dword v242, v[240:241], off
	global_load_dword v242, v[240:241], off offset:512
	s_mov_b64 s[98:99], 0x50000
	v_lshl_add_u64 v[240:241], v[240:241], 0, s[98:99]
	s_mov_b64 s[98:99], 0x10000
	global_load_dword v242, v[240:241], off
	global_load_dword v242, v[240:241], off offset:512
	v_lshl_add_u64 v[240:241], v[240:241], 0, s[98:99]
	global_load_dword v242, v[240:241], off
	global_load_dword v242, v[240:241], off offset:512
	v_lshl_add_u64 v[240:241], v[240:241], 0, s[98:99]
	global_load_dword v242, v[240:241], off
	global_load_dword v242, v[240:241], off offset:512
	v_lshl_add_u64 v[240:241], v[240:241], 0, s[98:99]
	global_load_dword v242, v[240:241], off
	global_load_dword v242, v[240:241], off offset:512
.Lpf_out_skip:
	v_mov_b32_e32 v150, 0
	v_mov_b32_e32 v151, 0
	v_mov_b32_e32 v148, 0
	v_mov_b32_e32 v149, 0
	v_mov_b32_e32 v154, 0
	v_mov_b32_e32 v155, 0
	v_mov_b32_e32 v152, 0
	v_mov_b32_e32 v153, 0
	s_and_saveexec_b64 s[26:27], vcc
	s_cbranch_execz .LBB0_385
	v_mov_b32_e32 v143, v185
	v_lshl_add_u64 v[148:149], v[156:157], 0, v[142:143]
	global_load_dwordx4 v[150:153], v[148:149], off
	global_load_dwordx4 v[160:163], v[148:149], off offset:16
	s_waitcnt vmcnt(0)
	v_pk_add_f32 v[148:149], v[126:127], v[152:153]
	v_pk_add_f32 v[150:151], v[124:125], v[150:151]
	v_pk_add_f32 v[152:153], v[122:123], v[162:163]
	v_pk_add_f32 v[154:155], v[120:121], v[160:161]
